# GEMM: static s_setprio 1 for waves 4-7 (younger half) on top of no per-phase flips
# baseline (speedup 1.0000x reference)
; #define PG8_STAGE(bufoff, gbase, voff) do { _Pragma("unroll") for (int _i = 0; _i < 2; ++_i) \
;     __builtin_amdgcn_global_load_lds((const unsigned*)((const char*)(gbase) + (voff)[_i]), (LAS unsigned*)(lds + (bufoff) + ldsw + _i * 8192), 16, 0, 0); } while (0)
; #define PG8_WAIT_V(n) asm volatile("s_waitcnt vmcnt(" #n ")" ::: "memory")
; #define PG8_BAR __builtin_amdgcn_s_barrier()
; template <class Epi>
; __device__ __forceinline__ void gemm_phase(LAS unsigned char* lds, const Gemm g, const StaticOrder& S, const Epi& E) {
;     ...
;   const int wid = __builtin_amdgcn_readfirstlane(tid >> 6), lane = tid & 63, wr = wid >> 2, wc = wid & 3, fr = lane & 15, fq = lane >> 4;
;   const int K = g.K, nt = K / BK;
;   unsigned voffA[2], voffB[2];
; #pragma unroll
;   for (int i = 0; i < 2; ++i) { int R, C; stage_rc(tid * 16 + i * 8192, R, C); const int Rb = (R & ~31) + perm32(R & 31);
;     voffA[i] = (unsigned)(R * K + C) * 2u; voffB[i] = (unsigned)(Rb * K + C) * 2u; }
;   const size_t kstep = (size_t)(BK * 2);
;   const size_t hstep = (size_t)HALF * K * 2;
;   const size_t tstep = 2 * hstep;
;   const unsigned ldsw = (unsigned)wid * 1024u;
;   const int aoff = lds_byte(wr * 64 + fr, fq * 8), boff = lds_byte(wc * 32 + fr, fq * 8);
;     ...
;   Unit cur, nxt; int ui = 0;
;   if (!S.next(0, cur)) return;
;   f32x4 acc[2][2][4][2];
; #pragma unroll
;   for (int a = 0; a < 2; ++a)
; #pragma unroll
;     for (int b = 0; b < 2; ++b)
; #pragma unroll
;       for (int m = 0; m < 4; ++m)
; #pragma unroll
;         for (int n = 0; n < 2; ++n) acc[a][b][m][n] = (f32x4){0.f, 0.f, 0.f, 0.f};
;   bf16x8 At[4][2], B0[2][2], B1[2][2];
;   const char* pAm = (const char*)g.A + (size_t)cur.pm * tstep; const char* pBn = (const char*)g.Bt + (size_t)cur.pn * tstep;
;   const char* cA = cur.swap ? pBn : pAm; const char* cB = cur.swap ? pAm : pBn;
;   PG8_STAGE(PG8_SB(0, 0), cB, voffB); PG8_STAGE(PG8_SA(0, 0), cA, voffA); PG8_STAGE(PG8_SB(0, 1), cB + hstep, voffB); PG8_STAGE(PG8_SA(0, 1), cA + hstep, voffA);
;   if (wr == 1) PG8_BAR;
;   PG8_WAIT_V(4); PG8_BAR;
;   PG8_STAGE(PG8_SB(1, 0), cB + kstep, voffB); PG8_STAGE(PG8_SA(1, 0), cA + kstep, voffA); PG8_STAGE(PG8_SB(1, 1), cB + hstep + kstep, voffB);
;   PG8_WAIT_V(6); PG8_BAR;
.LBB0_48:
	s_add_i32 m0, s15, 0x18000
	v_lshl_add_u64 v[0:1], v[0:1], 0, s[90:91]
	s_waitcnt vmcnt(4)
	s_barrier
	global_load_lds_dwordx4 v[0:1], off
	v_lshl_add_u64 v[0:1], v[2:3], 0, s[90:91]
	s_add_i32 m0, s15, 0x1a000
	s_add_i32 s29, s15, 0x8000
	global_load_lds_dwordx4 v[0:1], off
	v_lshl_add_u64 v[0:1], v[4:5], 0, s[90:91]
	s_mov_b32 m0, s29
	s_add_i32 s20, s15, 0xa000
	global_load_lds_dwordx4 v[0:1], off
	v_lshl_add_u64 v[0:1], v[6:7], 0, s[90:91]
	s_mov_b32 m0, s20
	v_bfe_u32 v19, v12, 4, 2
	global_load_lds_dwordx4 v[0:1], off
	s_add_i32 m0, s15, 0x1c000
	v_lshl_add_u64 v[0:1], v[8:9], 0, s[90:91]
	global_load_lds_dwordx4 v[0:1], off
	v_lshl_add_u64 v[0:1], v[10:11], 0, s[90:91]
	s_add_i32 m0, s15, 0x1e000
	v_and_b32_e32 v186, 15, v12
	global_load_lds_dwordx4 v[0:1], off
	v_lshlrev_b32_e32 v1, 4, v19
	v_lshlrev_b32_e32 v2, 2, v12
	s_and_b32 s11, s2, 3
	s_lshr_b32 s2, s1, 6
	v_lshl_or_b32 v1, v186, 6, v1
	s_lshl_b32 s1, s3, 13
	v_and_b32_e32 v2, 32, v2
	v_bitop3_b32 v3, v1, s1, v2 bitop3:0xde
	s_ashr_i32 s1, s0, 31
	s_lshl_b32 s28, s3, 6
	s_lshl_b32 s9, s11, 12
	s_add_i32 s21, s2, -2
	s_lshr_b32 s81, s92, 3
	s_lshl_b32 s12, s8, 3
	s_lshl_b64 s[4:5], s[0:1], 16
	s_add_u32 s3, s88, s4
	s_addc_u32 s10, s89, s5
	s_add_u32 s4, s3, 0x3f912100
	s_addc_u32 s5, s10, 0
	v_writelane_b32 v254, s4, 16
	v_bitop3_b32 v187, v1, s9, v2 bitop3:0xde
	v_lshlrev_b32_e32 v0, 3, v19
	v_writelane_b32 v254, s5, 17
	s_lshl_b32 s4, s0, 27
	s_and_b32 s4, s4, 0x8000000
	s_add_u32 s30, s88, 0x16852000
	s_addc_u32 s31, s89, 0
	s_add_u32 s4, s30, s4
	s_addc_u32 s5, s31, 0
	s_add_u32 s34, s88, 0xc300000
	v_writelane_b32 v254, s4, 23
	s_addc_u32 s35, s89, 0
	v_lshl_or_b32 v188, s11, 5, v0
	v_writelane_b32 v254, s5, 24
	s_add_u32 s4, s88, 0x16350000
	v_writelane_b32 v254, s4, 41
	s_addc_u32 s4, s89, 0
	v_writelane_b32 v254, s4, 14
	s_lshl_b32 s4, s0, 26
	s_and_b32 s6, s4, 0x4000000
	v_readlane_b32 s4, v254, 39
	v_readlane_b32 s5, v254, 40
	s_and_b64 s[4:5], s[4:5], exec
	s_cselect_b32 s4, 0x800, 0
	s_add_u32 s56, s88, s6
	s_addc_u32 s57, s89, 0
	s_add_u32 s4, s56, s4
	s_addc_u32 s5, s57, 0
	s_add_u32 s60, s4, 0x25852000
	s_addc_u32 s61, s5, 0
	s_lshl_b64 s[6:7], s[0:1], 25
	s_add_u32 s4, s88, s6
	s_addc_u32 s5, s89, s7
	s_add_u32 s4, s4, 0x35912000
	s_addc_u32 s5, s5, 0
	s_add_u32 s82, s3, 0x16300000
	s_addc_u32 s83, s10, 0
	s_add_u32 s68, s88, 0x1f852000
	s_addc_u32 s69, s89, 0
	v_writelane_b32 v254, s68, 30
	s_add_u32 s6, s34, s6
	s_addc_u32 s7, s35, s7
	v_writelane_b32 v254, s69, 31
	s_lshl_b64 s[0:1], s[0:1], 26
	v_readlane_b32 s68, v253, 0
	v_readlane_b32 s69, v253, 1
	s_add_u32 s0, s68, s0
	s_addc_u32 s1, s69, s1
	s_abs_i32 s3, s12
	v_cvt_f32_u32_e32 v4, s3
	v_writelane_b32 v254, s6, 18
	s_waitcnt vmcnt(6)
	v_readlane_b32 s70, v253, 2
	v_rcp_iflag_f32_e32 v1, v4
	v_writelane_b32 v254, s7, 19
	v_writelane_b32 v254, s0, 20
	s_mov_b32 s80, s12
	v_mul_f32_e32 v0, 0x4f7ffffe, v1
	v_cvt_u32_f32_e32 v0, v0
	v_writelane_b32 v254, s1, 21
	s_sub_i32 s0, 0, s3
	v_writelane_b32 v254, s11, 15
	v_readfirstlane_b32 s1, v0
	v_add_u32_e32 v0, v18, v16
	s_mul_i32 s0, s0, s1
	v_add_lshl_u32 v80, v0, v17, 1
	v_add_u32_e32 v0, v15, v13
	s_mul_hi_u32 s0, s1, s0
	v_lshl_add_u64 v[170:171], s[64:65], 0, v[80:81]
	v_add_lshl_u32 v80, v0, v14, 1
	s_mov_b32 s68, 0
	v_cmp_eq_u32_e64 s[6:7], 0, v19
	s_mov_b32 s93, s65
	s_bfe_i32 s69, s8, 0x1001c
	s_add_i32 s70, s1, s0
	v_lshl_add_u64 v[172:173], s[64:65], 0, v[80:81]
	v_add_u32_e32 v189, 0, v3
	v_readlane_b32 s71, v253, 3
	v_readlane_b32 s0, v254, 25
	s_nop 0
	s_cmpk_gt_u32 s0, 0xff
	s_cbranch_scc0 .Lprio_skip
	s_setprio 1
.Lprio_skip:
	s_barrier
	s_branch .LBB0_51

; #define PG8_WAIT_V(n) asm volatile("s_waitcnt vmcnt(" #n ")" ::: "memory")
; #define PG8_BAR __builtin_amdgcn_s_barrier()
; template <class Epi>
; __device__ __forceinline__ void gemm_phase(LAS unsigned char* lds, const Gemm g, const StaticOrder& S, const Epi& E) {
;     ...
;   PG8_WAIT_V(0);
;   if (wr == 0) PG8_BAR;
;   PG8_BAR;
.LBB0_350:
	s_setprio 0
	s_waitcnt vmcnt(0)
	v_readlane_b32 s0, v254, 25
	s_cmpk_gt_u32 s0, 0xff
	v_readlane_b32 s83, v254, 22
	s_cbranch_scc1 .LBB0_28
	s_barrier
	s_branch .LBB0_28
